# lean GEMM load segments + x->bf16 prologue loop with 8 loads in flight + attention queue order dilated units first
# baseline (speedup 1.0000x reference)
.LBB0_47:
	s_or_b64 exec, exec, s[10:11]
	s_waitcnt lgkmcnt(0)
	s_barrier
	ds_read_b32 v0, v239
	s_movk_i32 s10, 0x80
	s_waitcnt lgkmcnt(0)
	v_cmp_gt_i32_e32 vcc, s10, v0
	v_readfirstlane_b32 s90, v0
	s_mov_b64 s[10:11], -1
	s_cbranch_vccz .LBB0_94
	s_cmp_gt_u32 s90, 95
	s_cbranch_scc1 .Lq_remap_done
	s_add_i32 s20, s90, 48
	s_sub_i32 s21, s90, 48
	s_cmp_lt_u32 s90, 48
	s_cselect_b32 s90, s20, s21
.Lq_remap_done:
	s_cmp_gt_i32 s90, 47
	s_cbranch_scc0 .LBB0_96
	s_cmpk_gt_u32 s90, 0x5f
	s_cbranch_scc0 .LBB0_57
	s_lshl_b32 s10, s8, 1
	s_and_b32 s11, s90, 1
	s_and_b32 s10, s10, 2
	s_or_b32 s21, s11, s10
	s_lshl_b32 s10, s90, 7
	s_and_b32 s22, s10, 0x7fffff00
	s_lshr_b32 s20, s8, 1
	v_mov_b32_e32 v189, v240
	s_sub_i32 s72, s87, s22
	s_addk_i32 s72, 0x3f00
	v_and_b32_e32 v4, 31, v189
	s_mul_i32 s92, s20, 0x1800000
	v_or_b32_e32 v5, s72, v4
	s_lshl_b64 s[10:11], s[92:93], 1
	v_ashrrev_i32_e32 v2, 2, v189
	s_add_u32 s10, s84, s10
	v_lshl_add_u32 v188, s20, 12, v5
	v_mov_b64_e32 v[0:1], s[84:85]
	v_and_b32_e32 v2, -8, v2
	s_addc_u32 s11, s85, s11
	s_lshl_b32 s73, s21, 7
	s_lshl_b32 s92, s21, 8
	v_mad_i64_i32 v[0:1], s[20:21], v188, s33, v[0:1]
	v_ashrrev_i32_e32 v3, 31, v2
	s_add_u32 s10, s10, s92
	v_lshl_add_u64 v[0:1], v[0:1], 0, s[92:93]
	v_lshlrev_b64 v[2:3], 1, v[2:3]
	s_addc_u32 s11, s11, 0
	v_lshl_add_u64 v[0:1], v[0:1], 0, v[2:3]
	s_add_u32 s10, s10, 0x1000
	global_load_dwordx4 v[82:85], v[0:1], off
	global_load_dwordx4 v[86:89], v[0:1], off offset:32
	global_load_dwordx4 v[90:93], v[0:1], off offset:64
	global_load_dwordx4 v[94:97], v[0:1], off offset:96
	global_load_dwordx4 v[98:101], v[0:1], off offset:128
	global_load_dwordx4 v[102:105], v[0:1], off offset:160
	global_load_dwordx4 v[106:109], v[0:1], off offset:192
	global_load_dwordx4 v[110:113], v[0:1], off offset:224
	v_med3_i32 v0, v5, 0, v232
	s_addc_u32 s11, s11, 0
	v_mul_u32_u24_e32 v64, 0x3000, v0
	v_lshl_add_u64 v[0:1], s[10:11], 0, v[64:65]
	v_lshl_add_u64 v[0:1], v[0:1], 0, v[2:3]
	global_load_dwordx4 v[114:117], v[0:1], off
	global_load_dwordx4 v[118:121], v[0:1], off offset:32
	global_load_dwordx4 v[122:125], v[0:1], off offset:64
	global_load_dwordx4 v[126:129], v[0:1], off offset:96
	global_load_dwordx4 v[130:133], v[0:1], off offset:128
	global_load_dwordx4 v[134:137], v[0:1], off offset:160
	global_load_dwordx4 v[138:141], v[0:1], off offset:192
	global_load_dwordx4 v[142:145], v[0:1], off offset:224
	v_lshlrev_b32_e32 v7, 4, v189
	v_and_b32_e32 v64, 0xf0, v7
	v_and_b32_e32 v10, 64, v233
	v_lshl_add_u64 v[0:1], s[10:11], 0, v[64:65]
	s_mov_b64 s[20:21], 0x1000
	v_xor_b32_e32 v9, 32, v233
	v_add_u32_e32 v10, 64, v10
	v_lshl_add_u64 v[190:191], v[0:1], 0, s[20:21]
	v_lshlrev_b32_e32 v0, 7, v189
	v_lshlrev_b32_e32 v1, 2, v189
	v_cmp_lt_i32_e32 vcc, v9, v10
	v_ashrrev_i32_e32 v6, 5, v189
	v_and_b32_e32 v0, 0x600, v0
	v_and_b32_e32 v1, 0xffffffc0, v1
	v_cndmask_b32_e32 v9, v233, v9, vcc
	v_lshrrev_b32_e32 v10, 1, v189
	v_lshlrev_b32_e32 v5, 3, v189
	v_lshl_add_u64 v[192:193], s[10:11], 0, v[2:3]
	v_add3_u32 v0, s0, v0, v1
	v_and_b32_e32 v1, 48, v7
	v_bitop3_b32 v2, v7, 16, 48 bitop3:0x6c
	v_bitop3_b32 v3, v7, 32, 48 bitop3:0x6c
	v_bitop3_b32 v8, v7, 48, v7 bitop3:0xc
	v_lshlrev_b32_e32 v195, 2, v6
	v_lshlrev_b32_e32 v198, 2, v9
	v_lshlrev_b32_e32 v9, 8, v6
	v_and_b32_e32 v7, 0xc0, v7
	v_bitop3_b32 v6, v10, v6, 1 bitop3:0x6c
	v_lshlrev_b32_e32 v6, 4, v6
	v_and_b32_e32 v5, 8, v5
	v_add3_u32 v7, s0, v9, v7
	v_readlane_b32 s10, v255, 15
	v_add3_u32 v5, v7, v6, v5
	v_lshlrev_b32_e32 v6, 1, v189
	v_add_u32_e32 v4, s10, v4
	v_and_b32_e32 v7, 32, v6
	v_bitop3_b32 v6, v6, 32, v6 bitop3:0xc
	v_subrev_u32_e32 v4, s72, v4
	v_mov_b32_e32 v197, 0
	s_mov_b32 s17, s55
	s_ashr_i32 s74, s72, 5
	v_ashrrev_i32_e32 v247, 4, v189
	v_or_b32_e32 v248, 0xffffffe0, v189
	v_cmp_gt_u32_e64 s[20:21], 32, v189
	v_or_b32_e32 v199, 1, v195
	v_or_b32_e32 v200, 2, v195
	v_or_b32_e32 v201, 3, v195
	v_add_u32_e32 v202, 8, v195
	v_add_u32_e32 v203, 9, v195
	v_add_u32_e32 v216, 10, v195
	v_add_u32_e32 v217, 11, v195
	v_add_u32_e32 v218, 16, v195
	v_add_u32_e32 v219, 17, v195
	v_add_u32_e32 v220, 18, v195
	v_add_u32_e32 v221, 19, v195
	v_add_u32_e32 v222, 24, v195
	v_add_u32_e32 v223, 25, v195
	v_add_u32_e32 v224, 26, v195
	v_add_u32_e32 v225, 27, v195
	v_subrev_u32_e32 v249, s22, v4
	v_add_u32_e32 v241, v0, v1
	v_add_u32_e32 v242, v0, v2
	v_add_u32_e32 v243, v0, v3
	v_add_u32_e32 v244, v0, v8
	v_add_u32_e32 v245, v5, v7
	v_add_u32_e32 v246, v5, v6
	v_mov_b32_e32 v0, v197
	v_mov_b32_e32 v1, v197
	v_mov_b32_e32 v2, v197
	v_mov_b32_e32 v3, v197
	v_mov_b32_e32 v4, v197
	v_mov_b32_e32 v5, v197
	v_mov_b32_e32 v6, v197
	v_mov_b32_e32 v7, v197
	v_mov_b32_e32 v8, v197
	v_mov_b32_e32 v9, v197
	v_mov_b32_e32 v10, v197
	v_mov_b32_e32 v11, v197
	v_mov_b32_e32 v12, v197
	v_mov_b32_e32 v13, v197
	v_mov_b32_e32 v14, v197
	v_mov_b32_e32 v15, v197
	v_mov_b32_e32 v16, v197
	v_mov_b32_e32 v17, v197
	v_mov_b32_e32 v18, v197
	v_mov_b32_e32 v19, v197
	v_mov_b32_e32 v20, v197
	v_mov_b32_e32 v21, v197
	v_mov_b32_e32 v22, v197
	v_mov_b32_e32 v23, v197
	v_mov_b32_e32 v24, v197
	v_mov_b32_e32 v25, v197
	v_mov_b32_e32 v26, v197
	v_mov_b32_e32 v27, v197
	v_mov_b32_e32 v28, v197
	v_mov_b32_e32 v29, v197
	v_mov_b32_e32 v30, v197
	v_mov_b32_e32 v31, v197
	v_mov_b32_e32 v32, v197
	v_mov_b32_e32 v33, v197
	v_mov_b32_e32 v34, v197
	v_mov_b32_e32 v35, v197
	v_mov_b32_e32 v36, v197
	v_mov_b32_e32 v37, v197
	v_mov_b32_e32 v38, v197
	v_mov_b32_e32 v39, v197
	v_mov_b32_e32 v40, v197
	v_mov_b32_e32 v41, v197
	v_mov_b32_e32 v42, v197
	v_mov_b32_e32 v43, v197
	v_mov_b32_e32 v44, v197
	v_mov_b32_e32 v45, v197
	v_mov_b32_e32 v46, v197
	v_mov_b32_e32 v47, v197
	v_mov_b32_e32 v48, v197
	v_mov_b32_e32 v49, v197
	v_mov_b32_e32 v50, v197
	v_mov_b32_e32 v51, v197
	v_mov_b32_e32 v52, v197
	v_mov_b32_e32 v53, v197
	v_mov_b32_e32 v54, v197
	v_mov_b32_e32 v55, v197
	v_mov_b32_e32 v56, v197
	v_mov_b32_e32 v57, v197
	v_mov_b32_e32 v58, v197
	v_mov_b32_e32 v59, v197
	v_mov_b32_e32 v60, v197
	v_mov_b32_e32 v61, v197
	v_mov_b32_e32 v62, v197
	v_mov_b32_e32 v63, v197
	s_branch .LBB0_52
